# v_k9 + attention softmax VALU trimmed: max-subtract pairs fused into v_pk_add_f32 (DIFF), row-sum chains as packed partial sums (DIFF, GQA, MLA)
# speedup vs baseline: 1.0055x; 1.0015x over previous
; #define MFMA32(a, b, c) __builtin_amdgcn_mfma_f32_32x32x16_bf16((a), (b), (c), 0, 0, 0)
; template <int TYPE>
; DI void attn_item(const Params& p, int l, int bb, int head, int qb, char* smem) {
;     ...
;         const float mcur = mrun[mp];
; #pragma unroll
;         for (int kb = 0; kb < 2; kb++)
; #pragma unroll
;           for (int i = 0; i < 16; i++) { float e = __builtin_amdgcn_exp2f(s[kb][i] - mcur); s[kb][i] = e; psum += e; }
;       } else {
;         if (__builtin_amdgcn_ballot_w64(mx > 0.f) != 0ull) {
;           float delta = fmaxf(mx, 0.f);
;           float alpha = __builtin_amdgcn_exp2f(-delta);
;           mrun[mp] += delta;
;           lrun[mp] *= alpha;
; #pragma unroll
;           for (int d = 0; d < 2; d++)
; #pragma unroll
;             for (int i = 0; i < 16; i++) O[mp][d][i] *= alpha;
; #pragma unroll
;           for (int kb = 0; kb < 2; kb++)
; #pragma unroll
;             for (int i = 0; i < 16; i++) s[kb][i] -= delta;
;           const float nmv = -mrun[mp];
; #pragma unroll
;           for (int i = 0; i < 16; i++) nm[i] = nmv;
;         }
; #pragma unroll
;         for (int kb = 0; kb < 2; kb++)
; #pragma unroll
;           for (int i = 0; i < 16; i++) { float e = __builtin_amdgcn_exp2f(s[kb][i]); s[kb][i] = e; psum += e; }
;       }
;       lrun[mp] += psum;
; #pragma unroll
;       for (int kb = 0; kb < 2; kb++)
; #pragma unroll
;         for (int s2 = 0; s2 < 2; s2++) {
;           unsigned pw[4];
; #pragma unroll
;           for (int e = 0; e < 4; e++) pw[e] = pack2(s[kb][8 * s2 + 2 * e], s[kb][8 * s2 + 2 * e + 1]);
;           u32x4 pu = u32x4{pw[0], pw[1], pw[2], pw[3]};
;           bf16x8 pf = __builtin_bit_cast(bf16x8, pu);
; #pragma unroll
;           for (int d = 0; d < 2; d++) {
;             const u16* vp = sV + (d * 32 + r) * 72 + kb * 32 + s2 * 16 + 4 * h;
;             s16x4 vlo = *(const s16x4*)vp, vhi = *(const s16x4*)(vp + 8);
;             bf16x8 vf = __builtin_shufflevector(vlo, vhi, 0, 1, 2, 3, 4, 5, 6, 7);
;             O[mp][d] = MFMA32(vf, pf, O[mp][d]);
;           }
;         }
.LBB0_367:
	v_add_f32_e32 v240, 0, v183
	v_mov_b32_e32 v241, 0
	s_nop 0
	v_pk_add_f32 v[240:241], v[184:185], v[240:241]
	s_nop 0
	v_pk_add_f32 v[240:241], v[186:187], v[240:241]
	s_nop 0
	v_pk_add_f32 v[240:241], v[188:189], v[240:241]
	s_nop 0
	v_pk_add_f32 v[240:241], v[190:191], v[240:241]
	s_nop 0
	v_pk_add_f32 v[240:241], v[192:193], v[240:241]
	s_nop 0
	v_pk_add_f32 v[240:241], v[194:195], v[240:241]
	s_nop 0
	v_pk_add_f32 v[240:241], v[196:197], v[240:241]
	v_add_f32_e32 v240, v219, v240
	s_nop 0
	v_pk_add_f32 v[240:241], v[220:221], v[240:241]
	s_nop 0
	v_pk_add_f32 v[240:241], v[222:223], v[240:241]
	s_nop 0
	v_pk_add_f32 v[240:241], v[224:225], v[240:241]
	s_nop 0
	v_pk_add_f32 v[240:241], v[226:227], v[240:241]
	s_nop 0
	v_pk_add_f32 v[240:241], v[228:229], v[240:241]
	s_nop 0
	v_pk_add_f32 v[240:241], v[230:231], v[240:241]
	v_pk_add_f32 v[80:81], v[80:81], v[168:169] op_sel:[0,1] op_sel_hi:[1,1] neg_lo:[0,1] neg_hi:[0,1]
	s_nop 0
	v_exp_f32_e32 v80, v80
	s_nop 0
	v_pk_add_f32 v[240:241], v[232:233], v[240:241]
	v_exp_f32_e32 v81, v81
	v_pk_add_f32 v[82:83], v[82:83], v[168:169] op_sel:[0,1] op_sel_hi:[1,1] neg_lo:[0,1] neg_hi:[0,1]
	s_nop 0
	v_exp_f32_e32 v82, v82
	s_nop 0
	v_pk_add_f32 v[240:241], v[234:235], v[240:241]
	v_add_f32_e32 v183, v240, v241
	v_exp_f32_e32 v83, v83
	v_pk_add_f32 v[84:85], v[84:85], v[168:169] op_sel:[0,1] op_sel_hi:[1,1] neg_lo:[0,1] neg_hi:[0,1]
	v_add_f32_e32 v170, v170, v183
	v_mov_b64_e32 v[240:241], 0
	v_exp_f32_e32 v84, v84
	s_nop 0
	v_pk_add_f32 v[240:241], v[80:81], v[240:241]
	v_exp_f32_e32 v85, v85
	v_pk_add_f32 v[86:87], v[86:87], v[168:169] op_sel:[0,1] op_sel_hi:[1,1] neg_lo:[0,1] neg_hi:[0,1]
	s_nop 0
	v_exp_f32_e32 v86, v86
	s_nop 0
	v_pk_add_f32 v[240:241], v[82:83], v[240:241]
	v_exp_f32_e32 v87, v87
	v_pk_add_f32 v[88:89], v[88:89], v[168:169] op_sel:[0,1] op_sel_hi:[1,1] neg_lo:[0,1] neg_hi:[0,1]
	s_nop 0
	v_exp_f32_e32 v88, v88
	s_nop 0
	v_pk_add_f32 v[240:241], v[84:85], v[240:241]
	v_exp_f32_e32 v89, v89
	v_pk_add_f32 v[90:91], v[90:91], v[168:169] op_sel:[0,1] op_sel_hi:[1,1] neg_lo:[0,1] neg_hi:[0,1]
	s_nop 0
	v_exp_f32_e32 v90, v90
	s_nop 0
	v_pk_add_f32 v[240:241], v[86:87], v[240:241]
	v_exp_f32_e32 v91, v91
	v_pk_add_f32 v[92:93], v[92:93], v[168:169] op_sel:[0,1] op_sel_hi:[1,1] neg_lo:[0,1] neg_hi:[0,1]
	s_nop 0
	v_exp_f32_e32 v92, v92
	s_nop 0
	v_pk_add_f32 v[240:241], v[88:89], v[240:241]
	v_exp_f32_e32 v93, v93
	v_pk_add_f32 v[94:95], v[94:95], v[168:169] op_sel:[0,1] op_sel_hi:[1,1] neg_lo:[0,1] neg_hi:[0,1]
	s_nop 0
	v_exp_f32_e32 v94, v94
	s_nop 0
	v_pk_add_f32 v[240:241], v[90:91], v[240:241]
	v_exp_f32_e32 v95, v95
	v_pk_add_f32 v[64:65], v[64:65], v[168:169] op_sel:[0,1] op_sel_hi:[1,1] neg_lo:[0,1] neg_hi:[0,1]
	s_nop 0
	v_exp_f32_e32 v184, v64
	s_nop 0
	v_pk_add_f32 v[240:241], v[92:93], v[240:241]
	v_exp_f32_e32 v185, v65
	v_pk_add_f32 v[66:67], v[66:67], v[168:169] op_sel:[0,1] op_sel_hi:[1,1] neg_lo:[0,1] neg_hi:[0,1]
	s_nop 0
	v_exp_f32_e32 v186, v66
	s_nop 0
	v_pk_add_f32 v[240:241], v[94:95], v[240:241]
	v_exp_f32_e32 v187, v67
	s_nop 0
	v_pk_add_f32 v[240:241], v[184:185], v[240:241]
	s_nop 0
	v_pk_add_f32 v[240:241], v[186:187], v[240:241]
	v_cvt_pk_bf16_f32 v64, v80, v81
	v_cvt_pk_bf16_f32 v65, v82, v83
	v_cvt_pk_bf16_f32 v66, v84, v85
	v_cvt_pk_bf16_f32 v67, v86, v87
	v_pk_add_f32 v[68:69], v[68:69], v[168:169] op_sel:[0,1] op_sel_hi:[1,1] neg_lo:[0,1] neg_hi:[0,1]
	v_exp_f32_e32 v68, v68
	v_mfma_f32_32x32x16_bf16 v[48:63], v[132:135], v[64:67], v[48:63]
	s_nop 0
	v_exp_f32_e32 v69, v69
	v_pk_add_f32 v[70:71], v[70:71], v[168:169] op_sel:[0,1] op_sel_hi:[1,1] neg_lo:[0,1] neg_hi:[0,1]
	v_exp_f32_e32 v70, v70
	s_nop 0
	s_nop 0
	v_exp_f32_e32 v71, v71
	v_mfma_f32_32x32x16_bf16 v[16:31], v[136:139], v[64:67], v[16:31]
	v_pk_add_f32 v[240:241], v[68:69], v[240:241]
	s_nop 0
	v_cvt_pk_bf16_f32 v64, v88, v89
	v_cvt_pk_bf16_f32 v65, v90, v91
	v_cvt_pk_bf16_f32 v66, v92, v93
	v_cvt_pk_bf16_f32 v67, v94, v95
	v_pk_add_f32 v[72:73], v[72:73], v[168:169] op_sel:[0,1] op_sel_hi:[1,1] neg_lo:[0,1] neg_hi:[0,1]
	s_nop 0
	v_mfma_f32_32x32x16_bf16 v[48:63], v[128:131], v[64:67], v[48:63]
	v_pk_add_f32 v[240:241], v[70:71], v[240:241]
	v_exp_f32_e32 v72, v72
	v_exp_f32_e32 v73, v73
	s_add_i32 s12, s12, -1
	s_mov_b64 s[42:43], 0x2000
	s_nop 0
	v_pk_add_f32 v[240:241], v[72:73], v[240:241]
	v_mfma_f32_32x32x16_bf16 v[16:31], v[140:143], v[64:67], v[16:31]
	v_pk_add_f32 v[74:75], v[74:75], v[168:169] op_sel:[0,1] op_sel_hi:[1,1] neg_lo:[0,1] neg_hi:[0,1]
	v_exp_f32_e32 v74, v74
	v_cvt_pk_bf16_f32 v64, v184, v185
	v_cvt_pk_bf16_f32 v65, v186, v187
	v_cvt_pk_bf16_f32 v66, v68, v69
	v_cvt_pk_bf16_f32 v67, v70, v71
	s_nop 0
	v_pk_add_f32 v[76:77], v[76:77], v[168:169] op_sel:[0,1] op_sel_hi:[1,1] neg_lo:[0,1] neg_hi:[0,1]
	v_mfma_f32_32x32x16_bf16 v[48:63], v[144:147], v[64:67], v[48:63]
	s_nop 0
	v_pk_add_f32 v[78:79], v[78:79], v[168:169] op_sel:[0,1] op_sel_hi:[1,1] neg_lo:[0,1] neg_hi:[0,1]
	v_exp_f32_e32 v68, v75
	v_exp_f32_e32 v69, v76
	v_exp_f32_e32 v70, v77
	v_exp_f32_e32 v71, v78
	v_lshl_add_u64 v[160:161], v[160:161], 0, s[40:41]
	v_mfma_f32_32x32x16_bf16 v[16:31], v[148:151], v[64:67], v[16:31]
	s_nop 0
	v_exp_f32_e32 v75, v79
	v_cvt_pk_bf16_f32 v64, v72, v73
	v_cvt_pk_bf16_f32 v65, v74, v68
	v_cvt_pk_bf16_f32 v66, v69, v70
	v_cvt_pk_bf16_f32 v67, v71, v75
	v_add_f32_e32 v240, v74, v240
	v_add_f32_e32 v72, v240, v241
	v_add_f32_e32 v68, v68, v72
	v_mfma_f32_32x32x16_bf16 v[48:63], v[152:155], v[64:67], v[48:63]
	v_add_f32_e32 v68, v69, v68
	v_add_f32_e32 v68, v70, v68
	v_add_f32_e32 v68, v71, v68
	v_add_f32_e32 v68, v75, v68
	v_add_f32_e32 v168, v168, v68
	v_lshl_add_u64 v[162:163], v[162:163], 0, s[40:41]
	v_lshl_add_u64 v[164:165], v[164:165], 0, s[42:43]
	v_mfma_f32_32x32x16_bf16 v[16:31], v[156:159], v[64:67], v[16:31]
	s_cmp_eq_u32 s12, 0
	v_lshl_add_u64 v[166:167], v[166:167], 0, s[42:43]
	s_barrier
	s_cbranch_scc1 .LBB0_373

; template <int TYPE>
; DI void attn_item(const Params& p, int l, int bb, int head, int qb, char* smem) {
;     ...
;       for (int kb = 0; kb < 2; kb++) {
; #pragma unroll
;         for (int ks = 0; ks < NKS; ks++) {
;           bf16x8 kf = *(const bf16x8*)(sK + (kb * 32 + r) * KP + mp * 32 + ks * 16 + h * 8);
;           if (ks == 0) {
;             if (TYPE == 2) { f32x16 z; for (int i = 0; i < 16; i++) z[i] = 0.f; s[kb] = MFMA32(kf, qf[mp][ks], z); }
;             else s[kb] = MFMA32(kf, qf[mp][ks], nm);
;     ...
;         const float mcur = mrun[mp];
; #pragma unroll
;         for (int kb = 0; kb < 2; kb++)
; #pragma unroll
;           for (int i = 0; i < 16; i++) { float e = __builtin_amdgcn_exp2f(s[kb][i] - mcur); s[kb][i] = e; psum += e; }
;       } else {
;         if (__builtin_amdgcn_ballot_w64(mx > 0.f) != 0ull) {
;           float delta = fmaxf(mx, 0.f);
;           float alpha = __builtin_amdgcn_exp2f(-delta);
;           mrun[mp] += delta;
;           lrun[mp] *= alpha;
; #pragma unroll
;           for (int d = 0; d < 2; d++)
; #pragma unroll
;             for (int i = 0; i < 16; i++) O[mp][d][i] *= alpha;
; #pragma unroll
;           for (int kb = 0; kb < 2; kb++)
; #pragma unroll
;             for (int i = 0; i < 16; i++) s[kb][i] -= delta;
;           const float nmv = -mrun[mp];
; #pragma unroll
;           for (int i = 0; i < 16; i++) nm[i] = nmv;
;         }
; #pragma unroll
;         for (int kb = 0; kb < 2; kb++)
; #pragma unroll
;           for (int i = 0; i < 16; i++) { float e = __builtin_amdgcn_exp2f(s[kb][i]); s[kb][i] = e; psum += e; }
;       }
;       lrun[mp] += psum;
; #pragma unroll
;       for (int kb = 0; kb < 2; kb++)
; #pragma unroll
;         for (int s2 = 0; s2 < 2; s2++) {
;           unsigned pw[4];
; #pragma unroll
;           for (int e = 0; e < 4; e++) pw[e] = pack2(s[kb][8 * s2 + 2 * e], s[kb][8 * s2 + 2 * e + 1]);
;           u32x4 pu = u32x4{pw[0], pw[1], pw[2], pw[3]};
;           bf16x8 pf = __builtin_bit_cast(bf16x8, pu);
; #pragma unroll
;           for (int d = 0; d < 2; d++) {
;             const u16* vp = sV + (d * 32 + r) * 72 + kb * 32 + s2 * 16 + 4 * h;
;             s16x4 vlo = *(const s16x4*)vp, vhi = *(const s16x4*)(vp + 8);
;             bf16x8 vf = __builtin_shufflevector(vlo, vhi, 0, 1, 2, 3, 4, 5, 6, 7);
;             O[mp][d] = MFMA32(vf, pf, O[mp][d]);
;           }
;         }
.LBB0_370:
	v_pk_add_f32 v[64:65], v[64:65], v[174:175] op_sel_hi:[1,0] neg_lo:[0,1] neg_hi:[0,1]
	v_exp_f32_e32 v220, v64
	s_nop 0
	v_exp_f32_e32 v221, v65
	v_pk_add_f32 v[66:67], v[66:67], v[174:175] op_sel_hi:[1,0] neg_lo:[0,1] neg_hi:[0,1]
	v_exp_f32_e32 v222, v66
	s_nop 0
	v_pk_add_f32 v[80:81], v[80:81], v[174:175] op_sel_hi:[1,0] neg_lo:[0,1] neg_hi:[0,1]
	v_exp_f32_e32 v223, v67
	v_pk_add_f32 v[68:69], v[68:69], v[174:175] op_sel_hi:[1,0] neg_lo:[0,1] neg_hi:[0,1]
	v_exp_f32_e32 v183, v80
	s_nop 0
	v_exp_f32_e32 v224, v68
	s_nop 0
	v_exp_f32_e32 v184, v81
	v_pk_add_f32 v[82:83], v[82:83], v[174:175] op_sel_hi:[1,0] neg_lo:[0,1] neg_hi:[0,1]
	v_exp_f32_e32 v225, v69
	v_pk_add_f32 v[70:71], v[70:71], v[174:175] op_sel_hi:[1,0] neg_lo:[0,1] neg_hi:[0,1]
	v_exp_f32_e32 v185, v82
	s_nop 0
	v_exp_f32_e32 v226, v70
	s_nop 0
	v_add_u32_e32 v172, 0x2000, v182
	v_add_u32_e32 v173, 0x3000, v182
	v_exp_f32_e32 v186, v83
	v_pk_add_f32 v[84:85], v[84:85], v[174:175] op_sel_hi:[1,0] neg_lo:[0,1] neg_hi:[0,1]
	v_exp_f32_e32 v227, v71
	v_pk_add_f32 v[72:73], v[72:73], v[174:175] op_sel_hi:[1,0] neg_lo:[0,1] neg_hi:[0,1]
	ds_read2_b64 v[132:135], v172 offset0:128 offset1:130
	ds_read2_b64 v[128:131], v172 offset0:132 offset1:134
	ds_read2_b64 v[136:139], v173 offset0:192 offset1:194
	v_exp_f32_e32 v187, v84
	s_nop 0
	v_exp_f32_e32 v228, v72
	s_nop 0
	v_exp_f32_e32 v188, v85
	v_pk_add_f32 v[86:87], v[86:87], v[174:175] op_sel_hi:[1,0] neg_lo:[0,1] neg_hi:[0,1]
	v_exp_f32_e32 v229, v73
	v_pk_add_f32 v[74:75], v[74:75], v[174:175] op_sel_hi:[1,0] neg_lo:[0,1] neg_hi:[0,1]
	v_exp_f32_e32 v189, v86
	s_nop 0
	v_exp_f32_e32 v230, v74
	s_nop 0
	v_exp_f32_e32 v190, v87
	v_pk_add_f32 v[88:89], v[88:89], v[174:175] op_sel_hi:[1,0] neg_lo:[0,1] neg_hi:[0,1]
	v_exp_f32_e32 v231, v75
	v_pk_add_f32 v[76:77], v[76:77], v[174:175] op_sel_hi:[1,0] neg_lo:[0,1] neg_hi:[0,1]
	v_exp_f32_e32 v191, v88
	s_nop 0
	v_exp_f32_e32 v232, v76
	s_nop 0
	v_exp_f32_e32 v192, v89
	v_pk_add_f32 v[90:91], v[90:91], v[174:175] op_sel_hi:[1,0] neg_lo:[0,1] neg_hi:[0,1]
	v_exp_f32_e32 v233, v77
	v_pk_add_f32 v[78:79], v[78:79], v[174:175] op_sel_hi:[1,0] neg_lo:[0,1] neg_hi:[0,1]
	v_exp_f32_e32 v193, v90
	s_nop 0
	v_exp_f32_e32 v234, v78
	s_nop 0
	v_exp_f32_e32 v194, v91
	v_pk_add_f32 v[92:93], v[92:93], v[174:175] op_sel_hi:[1,0] neg_lo:[0,1] neg_hi:[0,1]
	v_exp_f32_e32 v235, v79
	v_cvt_pk_bf16_f32 v64, v183, v184
	v_cvt_pk_bf16_f32 v65, v185, v186
	v_cvt_pk_bf16_f32 v66, v187, v188
	v_cvt_pk_bf16_f32 v67, v189, v190
	ds_read2_b64 v[140:143], v173 offset0:196 offset1:198
	v_exp_f32_e32 v195, v92
	s_nop 0
	s_waitcnt lgkmcnt(3)
	v_mfma_f32_32x32x16_bf16 v[32:47], v[132:135], v[64:67], v[32:47]
	v_exp_f32_e32 v196, v93
	v_pk_add_f32 v[94:95], v[94:95], v[174:175] op_sel_hi:[1,0] neg_lo:[0,1] neg_hi:[0,1]
	v_exp_f32_e32 v197, v94
	s_nop 0
	v_exp_f32_e32 v219, v95
	ds_read2_b64 v[144:147], v172 offset0:136 offset1:138
	ds_read2_b64 v[148:151], v173 offset0:200 offset1:202
	s_waitcnt lgkmcnt(3)
	v_mfma_f32_32x32x16_bf16 v[0:15], v[136:139], v[64:67], v[0:15]
	v_cvt_pk_bf16_f32 v64, v191, v192
	v_cvt_pk_bf16_f32 v65, v193, v194
	v_cvt_pk_bf16_f32 v66, v195, v196
	v_cvt_pk_bf16_f32 v67, v197, v219
	ds_read2_b64 v[152:155], v172 offset0:140 offset1:142
	ds_read2_b64 v[156:159], v173 offset0:204 offset1:206
	v_mfma_f32_32x32x16_bf16 v[32:47], v[128:131], v[64:67], v[32:47]
	s_waitcnt lgkmcnt(4)
	v_mfma_f32_32x32x16_bf16 v[0:15], v[140:143], v[64:67], v[0:15]
	v_cvt_pk_bf16_f32 v64, v220, v221
	v_cvt_pk_bf16_f32 v65, v222, v223
	v_cvt_pk_bf16_f32 v66, v224, v225
	v_cvt_pk_bf16_f32 v67, v226, v227
	s_waitcnt lgkmcnt(3)
	s_nop 0
	v_mfma_f32_32x32x16_bf16 v[32:47], v[144:147], v[64:67], v[32:47]
	s_waitcnt lgkmcnt(2)
	v_mfma_f32_32x32x16_bf16 v[0:15], v[148:151], v[64:67], v[0:15]
	v_cvt_pk_bf16_f32 v64, v228, v229
	v_cvt_pk_bf16_f32 v65, v230, v231
	v_cvt_pk_bf16_f32 v66, v232, v233
	v_cvt_pk_bf16_f32 v67, v234, v235
	s_waitcnt lgkmcnt(1)
	s_nop 0
	v_mfma_f32_32x32x16_bf16 v[32:47], v[152:155], v[64:67], v[32:47]
	s_waitcnt lgkmcnt(0)
	v_mfma_f32_32x32x16_bf16 v[0:15], v[156:159], v[64:67], v[0:15]
	ds_read_b128 v[64:67], v171 offset:64
	ds_read_b128 v[68:71], v171 offset:96
	ds_read_b128 v[236:239], v171 offset:4704
	s_waitcnt lgkmcnt(2)
	v_mfma_f32_32x32x16_bf16 v[80:95], v[64:67], v[100:103], 0
	ds_read_b128 v[64:67], v171 offset:4672
	s_waitcnt lgkmcnt(2)
	v_mfma_f32_32x32x16_bf16 v[80:95], v[68:71], v[96:99], v[80:95]
	s_waitcnt lgkmcnt(0)
	v_mfma_f32_32x32x16_bf16 v[64:79], v[64:67], v[100:103], 0
	s_nop 9
	v_max_f32_e32 v202, v81, v81
	v_max_f32_e32 v203, v80, v80
	v_max_f32_e32 v202, v203, v202
	v_max3_f32 v202, v202, v82, v83
	v_max3_f32 v202, v202, v84, v85
	v_max3_f32 v202, v202, v86, v87
	v_max3_f32 v202, v202, v88, v89
	v_mfma_f32_32x32x16_bf16 v[64:79], v[236:239], v[96:99], v[64:79]
	v_max3_f32 v202, v202, v90, v91
	v_max3_f32 v202, v202, v92, v93
	v_max3_f32 v202, v202, v94, v95
	s_nop 8
	v_max3_f32 v202, v202, v64, v65
	v_max3_f32 v202, v202, v66, v67
	v_max3_f32 v202, v202, v68, v69
	v_max3_f32 v202, v202, v70, v71
	v_max3_f32 v202, v202, v72, v73
	v_max3_f32 v202, v202, v74, v75
	v_max3_f32 v202, v202, v76, v77
	v_max3_f32 v202, v202, v78, v79
	v_mov_b32_e32 v203, v202
	s_nop 1
	v_permlane32_swap_b32_e32 v202, v203
	v_max_f32_e32 v203, v203, v203
	v_max_f32_e32 v202, v202, v202
	v_max_f32_e32 v236, v202, v203
	v_cmp_gt_f32_e32 vcc, v236, v169
	s_cbranch_vccz .LBB0_367
	v_max_f32_e32 v202, v236, v236
	v_max_f32_e32 v203, v169, v169
	v_max_f32_e32 v203, v203, v202
	v_sub_f32_e32 v169, v169, v203
	v_exp_f32_e32 v202, v169
	v_mov_b32_e32 v169, v203
	v_mul_f32_e32 v168, v168, v202
	v_pk_mul_f32 v[62:63], v[62:63], v[202:203] op_sel_hi:[1,0]
	v_pk_mul_f32 v[60:61], v[60:61], v[202:203] op_sel_hi:[1,0]
	v_pk_mul_f32 v[58:59], v[58:59], v[202:203] op_sel_hi:[1,0]
	v_pk_mul_f32 v[56:57], v[56:57], v[202:203] op_sel_hi:[1,0]
	v_pk_mul_f32 v[54:55], v[54:55], v[202:203] op_sel_hi:[1,0]
	v_pk_mul_f32 v[52:53], v[52:53], v[202:203] op_sel_hi:[1,0]
	v_pk_mul_f32 v[50:51], v[50:51], v[202:203] op_sel_hi:[1,0]
	v_pk_mul_f32 v[48:49], v[48:49], v[202:203] op_sel_hi:[1,0]
	v_pk_mul_f32 v[30:31], v[30:31], v[202:203] op_sel_hi:[1,0]
	v_pk_mul_f32 v[28:29], v[28:29], v[202:203] op_sel_hi:[1,0]
	v_pk_mul_f32 v[26:27], v[26:27], v[202:203] op_sel_hi:[1,0]
	v_pk_mul_f32 v[24:25], v[24:25], v[202:203] op_sel_hi:[1,0]
	v_pk_mul_f32 v[22:23], v[22:23], v[202:203] op_sel_hi:[1,0]
	v_pk_mul_f32 v[20:21], v[20:21], v[202:203] op_sel_hi:[1,0]
	v_pk_mul_f32 v[18:19], v[18:19], v[202:203] op_sel_hi:[1,0]
	v_pk_mul_f32 v[16:17], v[16:17], v[202:203] op_sel_hi:[1,0]
	s_branch .LBB0_367

; #define MFMA32(a, b, c) __builtin_amdgcn_mfma_f32_32x32x16_bf16((a), (b), (c), 0, 0, 0)
; template <int TYPE>
; DI void attn_item(const Params& p, int l, int bb, int head, int qb, char* smem) {
;     ...
; #pragma unroll
;         for (int kb = 0; kb < 2; kb++)
; #pragma unroll
;           for (int i = 0; i < 16; i++) { float e = __builtin_amdgcn_exp2f(s[kb][i]); s[kb][i] = e; psum += e; }
;       }
;       lrun[mp] += psum;
; #pragma unroll
;       for (int kb = 0; kb < 2; kb++)
; #pragma unroll
;         for (int s2 = 0; s2 < 2; s2++) {
;           unsigned pw[4];
; #pragma unroll
;           for (int e = 0; e < 4; e++) pw[e] = pack2(s[kb][8 * s2 + 2 * e], s[kb][8 * s2 + 2 * e + 1]);
;           u32x4 pu = u32x4{pw[0], pw[1], pw[2], pw[3]};
;           bf16x8 pf = __builtin_bit_cast(bf16x8, pu);
; #pragma unroll
;           for (int d = 0; d < 2; d++) {
;             const u16* vp = sV + (d * 32 + r) * 72 + kb * 32 + s2 * 16 + 4 * h;
;             s16x4 vlo = *(const s16x4*)vp, vhi = *(const s16x4*)(vp + 8);
;             bf16x8 vf = __builtin_shufflevector(vlo, vhi, 0, 1, 2, 3, 4, 5, 6, 7);
;             O[mp][d] = MFMA32(vf, pf, O[mp][d]);
;           }
;         }
.LBB0_381:
	v_exp_f32_e32 v145, v80
	v_exp_f32_e32 v81, v81
	v_exp_f32_e32 v146, v82
	v_exp_f32_e32 v147, v83
	v_add_f32_e32 v240, 0, v145
	v_mov_b32_e32 v241, 0
	v_exp_f32_e32 v148, v84
	v_add_f32_e32 v240, v81, v240
	v_exp_f32_e32 v149, v85
	v_add_f32_e32 v240, v146, v240
	v_exp_f32_e32 v150, v86
	v_add_f32_e32 v240, v147, v240
	v_exp_f32_e32 v151, v87
	s_nop 0
	v_exp_f32_e32 v152, v88
	v_pk_add_f32 v[240:241], v[148:149], v[240:241]
	v_exp_f32_e32 v153, v89
	s_nop 0
	v_exp_f32_e32 v154, v90
	v_pk_add_f32 v[240:241], v[150:151], v[240:241]
	v_exp_f32_e32 v155, v91
	s_nop 0
	v_exp_f32_e32 v156, v92
	v_pk_add_f32 v[240:241], v[152:153], v[240:241]
	v_exp_f32_e32 v157, v93
	s_nop 0
	v_exp_f32_e32 v94, v94
	v_pk_add_f32 v[240:241], v[154:155], v[240:241]
	s_nop 0
	v_pk_add_f32 v[240:241], v[156:157], v[240:241]
	s_nop 0
	v_add_u32_e32 v80, 0x2000, v143
	ds_read2_b64 v[82:85], v80 offset0:128 offset1:130
	v_exp_f32_e32 v95, v95
	v_cvt_pk_bf16_f32 v86, v145, v81
	v_add_u32_e32 v81, 0x3000, v143
	v_exp_f32_e32 v159, v48
	ds_read2_b64 v[90:93], v81 offset0:192 offset1:194
	v_exp_f32_e32 v160, v49
	v_exp_f32_e32 v145, v50
	v_pk_add_f32 v[240:241], v[94:95], v[240:241]
	v_add_f32_e32 v240, v159, v240
	v_add_f32_e32 v240, v160, v240
	v_cvt_pk_bf16_f32 v87, v146, v147
	v_cvt_pk_bf16_f32 v88, v148, v149
	v_cvt_pk_bf16_f32 v89, v150, v151
	v_add_f32_e32 v240, v145, v240
	v_exp_f32_e32 v147, v51
	ds_read2_b64 v[48:51], v80 offset0:132 offset1:134
	s_waitcnt lgkmcnt(2)
	v_mfma_f32_32x32x16_bf16 v[16:31], v[82:85], v[86:89], v[16:31]
	v_cvt_pk_bf16_f32 v82, v152, v153
	v_cvt_pk_bf16_f32 v83, v154, v155
	v_cvt_pk_bf16_f32 v84, v156, v157
	v_cvt_pk_bf16_f32 v85, v94, v95
	v_exp_f32_e32 v55, v55
	v_exp_f32_e32 v56, v56
	v_exp_f32_e32 v60, v60
	s_waitcnt lgkmcnt(1)
	v_mfma_f32_32x32x16_bf16 v[0:15], v[90:93], v[86:89], v[0:15]
	ds_read2_b64 v[86:89], v81 offset0:196 offset1:198
	v_exp_f32_e32 v90, v52
	v_exp_f32_e32 v91, v53
	v_exp_f32_e32 v92, v54
	v_cvt_pk_bf16_f32 v53, v145, v147
	v_exp_f32_e32 v61, v61
	v_cvt_pk_bf16_f32 v54, v90, v91
	s_waitcnt lgkmcnt(1)
	v_mfma_f32_32x32x16_bf16 v[16:31], v[48:51], v[82:85], v[16:31]
	v_add_f32_e32 v240, v147, v240
	s_nop 0
	v_pk_add_f32 v[240:241], v[90:91], v[240:241]
	v_add_f32_e32 v240, v92, v240
	ds_read2_b64 v[48:51], v80 offset0:136 offset1:138
	v_exp_f32_e32 v62, v62
	v_exp_f32_e32 v63, v63
	s_waitcnt lgkmcnt(1)
	v_mfma_f32_32x32x16_bf16 v[0:15], v[86:89], v[82:85], v[0:15]
	ds_read2_b64 v[82:85], v81 offset0:200 offset1:202
	v_exp_f32_e32 v87, v57
	v_add_f32_e32 v240, v55, v240
	v_cvt_pk_bf16_f32 v52, v159, v160
	v_cvt_pk_bf16_f32 v55, v92, v55
	v_add_f32_e32 v240, v56, v240
	v_exp_f32_e32 v88, v58
	s_waitcnt lgkmcnt(1)
	v_mfma_f32_32x32x16_bf16 v[16:31], v[48:51], v[52:55], v[16:31]
	v_exp_f32_e32 v89, v59
	ds_read2_b64 v[48:51], v80 offset0:140 offset1:142
	s_add_i32 s12, s12, -1
	s_mov_b64 s[42:43], 0x2000
	v_lshl_add_u64 v[128:129], v[128:129], 0, s[40:41]
	v_lshl_add_u64 v[130:131], v[130:131], 0, s[40:41]
	v_lshl_add_u64 v[132:133], v[132:133], 0, s[42:43]
	s_waitcnt lgkmcnt(1)
	v_mfma_f32_32x32x16_bf16 v[0:15], v[82:85], v[52:55], v[0:15]
	v_cvt_pk_bf16_f32 v52, v56, v87
	ds_read2_b64 v[56:59], v81 offset0:204 offset1:206
	v_cvt_pk_bf16_f32 v53, v88, v89
	v_cvt_pk_bf16_f32 v54, v60, v61
	v_cvt_pk_bf16_f32 v55, v62, v63
	s_cmp_eq_u32 s12, 0
	v_lshl_add_u64 v[134:135], v[134:135], 0, s[42:43]
	s_waitcnt lgkmcnt(1)
	v_mfma_f32_32x32x16_bf16 v[16:31], v[48:51], v[52:55], v[16:31]
	v_add_f32_e32 v240, v87, v240
	s_nop 0
	v_pk_add_f32 v[240:241], v[88:89], v[240:241]
	s_nop 0
	v_pk_add_f32 v[240:241], v[60:61], v[240:241]
	s_nop 0
	v_pk_add_f32 v[240:241], v[62:63], v[240:241]
	v_add_f32_e32 v48, v240, v241
	s_waitcnt lgkmcnt(0)
	v_mfma_f32_32x32x16_bf16 v[0:15], v[56:59], v[52:55], v[0:15]
	v_add_f32_e32 v136, v136, v48
	s_barrier
	s_cbranch_scc1 .LBB0_384

; #define MFMA32(a, b, c) __builtin_amdgcn_mfma_f32_32x32x16_bf16((a), (b), (c), 0, 0, 0)
; template <int TYPE>
; DI void attn_item(const Params& p, int l, int bb, int head, int qb, char* smem) {
;     ...
; #pragma unroll
;         for (int kb = 0; kb < 2; kb++)
; #pragma unroll
;           for (int i = 0; i < 16; i++) { float e = __builtin_amdgcn_exp2f(s[kb][i]); s[kb][i] = e; psum += e; }
;       }
;       lrun[mp] += psum;
; #pragma unroll
;       for (int kb = 0; kb < 2; kb++)
; #pragma unroll
;         for (int s2 = 0; s2 < 2; s2++) {
;           unsigned pw[4];
; #pragma unroll
;           for (int e = 0; e < 4; e++) pw[e] = pack2(s[kb][8 * s2 + 2 * e], s[kb][8 * s2 + 2 * e + 1]);
;           u32x4 pu = u32x4{pw[0], pw[1], pw[2], pw[3]};
;           bf16x8 pf = __builtin_bit_cast(bf16x8, pu);
; #pragma unroll
;           for (int d = 0; d < 2; d++) {
;             const u16* vp = sV + (d * 32 + r) * 72 + kb * 32 + s2 * 16 + 4 * h;
;             s16x4 vlo = *(const s16x4*)vp, vhi = *(const s16x4*)(vp + 8);
;             bf16x8 vf = __builtin_shufflevector(vlo, vhi, 0, 1, 2, 3, 4, 5, 6, 7);
;             O[mp][d] = MFMA32(vf, pf, O[mp][d]);
;           }
;         }
.LBB0_391:
	v_exp_f32_e32 v160, v80
	v_exp_f32_e32 v81, v81
	v_exp_f32_e32 v161, v82
	v_exp_f32_e32 v162, v83
	v_mov_b64_e32 v[240:241], 0
	v_exp_f32_e32 v163, v84
	v_add_f32_e32 v240, v81, v240
	v_exp_f32_e32 v164, v85
	v_pk_add_f32 v[240:241], v[160:161], v[240:241]
	v_exp_f32_e32 v165, v86
	s_nop 0
	v_exp_f32_e32 v166, v87
	v_pk_add_f32 v[240:241], v[162:163], v[240:241]
	v_exp_f32_e32 v167, v88
	s_nop 0
	v_exp_f32_e32 v168, v89
	v_pk_add_f32 v[240:241], v[164:165], v[240:241]
	v_exp_f32_e32 v169, v90
	s_nop 0
	v_exp_f32_e32 v170, v91
	v_pk_add_f32 v[240:241], v[166:167], v[240:241]
	v_exp_f32_e32 v171, v92
	s_nop 0
	v_exp_f32_e32 v172, v93
	v_pk_add_f32 v[240:241], v[168:169], v[240:241]
	v_exp_f32_e32 v94, v94
	s_nop 0
	v_pk_add_f32 v[240:241], v[170:171], v[240:241]
	v_add_f32_e32 v240, v172, v240
	s_nop 0
	v_add_u32_e32 v80, 0x3000, v158
	ds_read2_b64 v[82:85], v80 offset0:128 offset1:130
	v_exp_f32_e32 v95, v95
	v_exp_f32_e32 v174, v48
	v_cvt_pk_bf16_f32 v86, v160, v81
	v_add_u32_e32 v81, 0x3000, v159
	v_exp_f32_e32 v175, v49
	ds_read2_b64 v[90:93], v81 offset0:128 offset1:130
	v_exp_f32_e32 v160, v50
	v_pk_add_f32 v[240:241], v[94:95], v[240:241]
	s_nop 0
	v_pk_add_f32 v[240:241], v[174:175], v[240:241]
	v_cvt_pk_bf16_f32 v87, v161, v162
	v_cvt_pk_bf16_f32 v88, v163, v164
	v_cvt_pk_bf16_f32 v89, v165, v166
	v_add_f32_e32 v240, v160, v240
	v_exp_f32_e32 v162, v51
	ds_read2_b64 v[48:51], v80 offset0:132 offset1:134
	s_waitcnt lgkmcnt(2)
	v_mfma_f32_32x32x16_bf16 v[16:31], v[82:85], v[86:89], v[16:31]
	ds_read2_b64 v[82:85], v81 offset0:132 offset1:134
	v_exp_f32_e32 v55, v55
	v_exp_f32_e32 v56, v56
	v_exp_f32_e32 v60, v60
	v_exp_f32_e32 v61, v61
	v_exp_f32_e32 v62, v62
	v_exp_f32_e32 v63, v63
	s_waitcnt lgkmcnt(2)
	v_mfma_f32_32x32x16_bf16 v[0:15], v[90:93], v[86:89], v[0:15]
	v_exp_f32_e32 v90, v52
	v_exp_f32_e32 v91, v53
	v_cvt_pk_bf16_f32 v86, v167, v168
	v_cvt_pk_bf16_f32 v87, v169, v170
	v_cvt_pk_bf16_f32 v88, v171, v172
	v_cvt_pk_bf16_f32 v89, v94, v95
	v_exp_f32_e32 v92, v54
	v_cvt_pk_bf16_f32 v53, v160, v162
	s_waitcnt lgkmcnt(1)
	v_mfma_f32_32x32x16_bf16 v[16:31], v[48:51], v[86:89], v[16:31]
	v_add_f32_e32 v240, v162, v240
	s_nop 0
	v_pk_add_f32 v[240:241], v[90:91], v[240:241]
	v_add_f32_e32 v240, v92, v240
	ds_read2_b64 v[48:51], v80 offset0:136 offset1:138
	v_cvt_pk_bf16_f32 v54, v90, v91
	s_add_u32 s0, s0, 0x3000
	s_waitcnt lgkmcnt(1)
	v_mfma_f32_32x32x16_bf16 v[0:15], v[82:85], v[86:89], v[0:15]
	ds_read2_b64 v[82:85], v81 offset0:136 offset1:138
	v_exp_f32_e32 v87, v57
	v_add_f32_e32 v240, v55, v240
	v_cvt_pk_bf16_f32 v52, v174, v175
	v_cvt_pk_bf16_f32 v55, v92, v55
	v_add_f32_e32 v240, v56, v240
	v_exp_f32_e32 v88, v58
	s_waitcnt lgkmcnt(1)
	v_mfma_f32_32x32x16_bf16 v[16:31], v[48:51], v[52:55], v[16:31]
	v_exp_f32_e32 v89, v59
	ds_read2_b64 v[48:51], v80 offset0:140 offset1:142
	s_addc_u32 s1, s1, 0
	v_lshl_add_u64 v[140:141], v[140:141], 0, s[40:41]
	s_cmp_eq_u32 s12, s0
	v_lshl_add_u64 v[142:143], v[142:143], 0, s[40:41]
	s_waitcnt lgkmcnt(1)
	v_mfma_f32_32x32x16_bf16 v[0:15], v[82:85], v[52:55], v[0:15]
	v_cvt_pk_bf16_f32 v52, v56, v87
	ds_read2_b64 v[56:59], v81 offset0:140 offset1:142
	v_cvt_pk_bf16_f32 v53, v88, v89
	v_cvt_pk_bf16_f32 v54, v60, v61
	v_cvt_pk_bf16_f32 v55, v62, v63
	s_waitcnt lgkmcnt(0)
	s_barrier
	v_mfma_f32_32x32x16_bf16 v[16:31], v[48:51], v[52:55], v[16:31]
	v_add_f32_e32 v240, v87, v240
	s_nop 0
	v_pk_add_f32 v[240:241], v[88:89], v[240:241]
	s_nop 0
	v_pk_add_f32 v[240:241], v[60:61], v[240:241]
	s_nop 0
	v_pk_add_f32 v[240:241], v[62:63], v[240:241]
	v_add_f32_e32 v48, v240, v241
	v_mfma_f32_32x32x16_bf16 v[0:15], v[56:59], v[52:55], v[0:15]
	v_add_f32_e32 v150, v150, v48
	s_cbranch_scc1 .LBB0_404
